# prep K convert / K zero rows / window copy relocated to IN idle tail (WGs>=90), hand-unrolled loads-first
# baseline (speedup 1.0000x reference)
; __device__ __forceinline__ unsigned pk2(float lo, float hi) { f32x2 v = {lo, hi}; bf16v2_t b = __builtin_convertvector(v, bf16v2_t); return __builtin_bit_cast(unsigned, b); }
; __device__ __forceinline__ void prep_phase(const Params& p, char* lds) {
;     ...
;     for (int i = gt; i < 128 * 128 * 16; i += NGT) {
;       const int c8 = i & 15, w = (i >> 4) & 127, b = i >> 11;
;       const float* s = ck + ((size_t)b * 128 + w) * 128 + c8 * 8;
;       const f32x4 a = *(const f32x4*)s, bq = *(const f32x4*)(s + 4);
;       u32x4 o; o.x = pk2(a.x, a.y); o.y = pk2(a.z, a.w); o.z = pk2(bq.x, bq.y); o.w = pk2(bq.z, bq.w);
;       *(u32x4*)(Ks + ((size_t)b * 144 + w) * 128 + c8 * 8) = o;
;     }
;     for (int i = gt; i < 128 * 12 * 16; i += NGT) {
;       const int c8 = i & 15, r = (i >> 4) % 12, b = i / 192;
;       *(u32x4*)(Ks + ((size_t)b * 144 + 132 + r) * 128 + c8 * 8) = u32x4{0u, 0u, 0u, 0u};
;     }
.LBB0_448:
	s_waitcnt vmcnt(0)
	s_waitcnt vmcnt(0)
	s_barrier
	v_readlane_b32 s98, v244, 33
	s_nop 3
	s_cmp_eq_u32 s33, 0x100
	s_cselect_b32 s99, 90, 0
	s_cmp_lt_u32 s98, s99
	s_cbranch_scc1 .Lkvc_skip
	v_writelane_b32 v246, s0, 0
	v_writelane_b32 v246, s1, 1
	v_writelane_b32 v246, s2, 2
	v_writelane_b32 v246, s3, 3
	v_writelane_b32 v246, s4, 4
	v_writelane_b32 v246, s5, 5
	v_writelane_b32 v246, s6, 6
	v_writelane_b32 v246, s7, 7
	v_writelane_b32 v246, s8, 8
	v_writelane_b32 v246, s9, 9
	v_writelane_b32 v246, s10, 10
	v_writelane_b32 v246, s11, 11
	v_writelane_b32 v246, s12, 12
	v_writelane_b32 v246, s13, 13
	v_writelane_b32 v246, s14, 14
	v_writelane_b32 v246, s15, 15
	v_writelane_b32 v246, s16, 16
	v_writelane_b32 v246, s17, 17
	v_writelane_b32 v246, s18, 18
	v_writelane_b32 v246, s19, 19
	v_writelane_b32 v246, s20, 20
	v_writelane_b32 v246, s21, 21
	v_writelane_b32 v246, s22, 22
	v_writelane_b32 v246, s23, 23
	v_writelane_b32 v246, s24, 24
	v_writelane_b32 v246, s25, 25
	s_sub_u32 s98, s98, s99
	v_lshlrev_b32_e32 v247, 3, v0
	v_lshl_or_b32 v245, s98, 9, v0
	s_sub_u32 s100, s33, s99
	s_lshl_b32 s101, s100, 9
	v_readlane_b32 s12, v244, 18
	v_readlane_b32 s13, v244, 19
	v_readlane_b32 s6, v244, 2
	v_readlane_b32 s7, v244, 3
	s_nop 1
	s_add_u32 s24, s6, 0xad00000
	s_addc_u32 s25, s7, 0
	v_mov_b32_e32 v20, v245
	s_mov_b32 s10, 0x9000
.Lkvc_l1:
	v_mov_b32_e32 v21, s101
	v_mad_u32_u24 v21, v21, 0, v20
	v_and_b32_e32 v22, 15, v21
	v_bfe_u32 v23, v21, 4, 7
	v_lshrrev_b32_e32 v19, 11, v21
	v_lshlrev_b32_e32 v18, 5, v22
	v_lshl_add_u32 v18, v23, 9, v18
	v_lshlrev_b32_e32 v17, 4, v22
	v_lshl_add_u32 v17, v23, 8, v17
	v_lshl_add_u32 v22, v19, 16, v18
	v_mad_u32_u24 v23, v19, s10, v17
	v_mov_b32_e32 v25, s101
	v_mad_u32_u24 v25, v25, 1, v20
	v_and_b32_e32 v26, 15, v25
	v_bfe_u32 v27, v25, 4, 7
	v_lshrrev_b32_e32 v19, 11, v25
	v_lshlrev_b32_e32 v18, 5, v26
	v_lshl_add_u32 v18, v27, 9, v18
	v_lshlrev_b32_e32 v17, 4, v26
	v_lshl_add_u32 v17, v27, 8, v17
	v_lshl_add_u32 v26, v19, 16, v18
	v_mad_u32_u24 v27, v19, s10, v17
	v_mov_b32_e32 v29, s101
	v_mad_u32_u24 v29, v29, 2, v20
	v_and_b32_e32 v30, 15, v29
	v_bfe_u32 v31, v29, 4, 7
	v_lshrrev_b32_e32 v19, 11, v29
	v_lshlrev_b32_e32 v18, 5, v30
	v_lshl_add_u32 v18, v31, 9, v18
	v_lshlrev_b32_e32 v17, 4, v30
	v_lshl_add_u32 v17, v31, 8, v17
	v_lshl_add_u32 v30, v19, 16, v18
	v_mad_u32_u24 v31, v19, s10, v17
	v_mov_b32_e32 v33, s101
	v_mad_u32_u24 v33, v33, 3, v20
	v_and_b32_e32 v34, 15, v33
	v_bfe_u32 v35, v33, 4, 7
	v_lshrrev_b32_e32 v19, 11, v33
	v_lshlrev_b32_e32 v18, 5, v34
	v_lshl_add_u32 v18, v35, 9, v18
	v_lshlrev_b32_e32 v17, 4, v34
	v_lshl_add_u32 v17, v35, 8, v17
	v_lshl_add_u32 v34, v19, 16, v18
	v_mad_u32_u24 v35, v19, s10, v17
	v_cmp_gt_u32_e32 vcc, 0x40000, v21
	s_and_saveexec_b64 s[4:5], vcc
	global_load_dwordx4 v[40:43], v22, s[12:13]
	global_load_dwordx4 v[44:47], v22, s[12:13] offset:16
	s_or_b64 exec, exec, s[4:5]
	v_cmp_gt_u32_e32 vcc, 0x40000, v25
	s_and_saveexec_b64 s[4:5], vcc
	global_load_dwordx4 v[48:51], v26, s[12:13]
	global_load_dwordx4 v[52:55], v26, s[12:13] offset:16
	s_or_b64 exec, exec, s[4:5]
	v_cmp_gt_u32_e32 vcc, 0x40000, v29
	s_and_saveexec_b64 s[4:5], vcc
	global_load_dwordx4 v[56:59], v30, s[12:13]
	global_load_dwordx4 v[60:63], v30, s[12:13] offset:16
	s_or_b64 exec, exec, s[4:5]
	v_cmp_gt_u32_e32 vcc, 0x40000, v33
	s_and_saveexec_b64 s[4:5], vcc
	global_load_dwordx4 v[64:67], v34, s[12:13]
	global_load_dwordx4 v[68:71], v34, s[12:13] offset:16
	s_or_b64 exec, exec, s[4:5]
	s_waitcnt vmcnt(0)
	v_cvt_pk_bf16_f32 v40, v40, v41
	v_cvt_pk_bf16_f32 v41, v42, v43
	v_cvt_pk_bf16_f32 v42, v44, v45
	v_cvt_pk_bf16_f32 v43, v46, v47
	v_cvt_pk_bf16_f32 v48, v48, v49
	v_cvt_pk_bf16_f32 v49, v50, v51
	v_cvt_pk_bf16_f32 v50, v52, v53
	v_cvt_pk_bf16_f32 v51, v54, v55
	v_cvt_pk_bf16_f32 v56, v56, v57
	v_cvt_pk_bf16_f32 v57, v58, v59
	v_cvt_pk_bf16_f32 v58, v60, v61
	v_cvt_pk_bf16_f32 v59, v62, v63
	v_cvt_pk_bf16_f32 v64, v64, v65
	v_cvt_pk_bf16_f32 v65, v66, v67
	v_cvt_pk_bf16_f32 v66, v68, v69
	v_cvt_pk_bf16_f32 v67, v70, v71
	v_cmp_gt_u32_e32 vcc, 0x40000, v21
	s_and_saveexec_b64 s[4:5], vcc
	global_store_dwordx4 v23, v[40:43], s[24:25]
	s_or_b64 exec, exec, s[4:5]
	v_cmp_gt_u32_e32 vcc, 0x40000, v25
	s_and_saveexec_b64 s[4:5], vcc
	global_store_dwordx4 v27, v[48:51], s[24:25]
	s_or_b64 exec, exec, s[4:5]
	v_cmp_gt_u32_e32 vcc, 0x40000, v29
	s_and_saveexec_b64 s[4:5], vcc
	global_store_dwordx4 v31, v[56:59], s[24:25]
	s_or_b64 exec, exec, s[4:5]
	v_cmp_gt_u32_e32 vcc, 0x40000, v33
	s_and_saveexec_b64 s[4:5], vcc
	global_store_dwordx4 v35, v[64:67], s[24:25]
	s_or_b64 exec, exec, s[4:5]
	v_mov_b32_e32 v19, s101
	v_mad_u32_u24 v20, v19, 4, v20
	v_cmp_gt_u32_e32 vcc, 0x40000, v20
	s_cbranch_vccnz .Lkvc_l1
	s_mov_b64 s[14:15], s[24:25]
	s_movk_i32 s3, 0x6000
	v_cmp_gt_i32_e32 vcc, s3, v245
	s_and_saveexec_b64 s[4:5], vcc
	s_cbranch_execz .Lkvc_46
	v_readlane_b32 s3, v244, 33
	s_nop 3
	s_sub_u32 s3, s3, s99
	v_mov_b32_e32 v3, 0
	s_mov_b64 s[6:7], 0
	v_lshl_or_b32 v1, s3, 12, v247
	s_lshl_b32 s3, s100, 12
	s_mov_b32 s8, 0x2aaaaaab
	s_movk_i32 s9, 0x90
	v_mov_b32_e32 v6, v3
	v_mov_b32_e32 v7, v3
	v_mov_b32_e32 v8, v3
	v_mov_b32_e32 v9, v3
	s_movk_i32 s10, 0x5fff
	v_mov_b32_e32 v4, v245

; __device__ __forceinline__ void prep_phase(const Params& p, char* lds) {
;     ...
;     for (int i = gt; i < 128 * 124 * 32; i += NGT) {
;       const int c4 = i & 31, w = (i >> 5) % 124, b = i / (124 * 32);
;       const size_t so = ((size_t)b * 128 + w + 4) * 128 + c4 * 4, dof = ((size_t)b * 128 + w) * 128 + c4 * 4;
;       *(f32x4*)(p.out + O_KS + dof) = *(const f32x4*)(ck + so);
;       *(f32x4*)(p.out + O_VS + dof) = *(const f32x4*)(cv + so);
;     }
.Lkvc_46:
	s_or_b64 exec, exec, s[4:5]
	v_readlane_b32 s12, v244, 18
	v_readlane_b32 s13, v244, 19
	v_readlane_b32 s14, v244, 20
	v_readlane_b32 s15, v244, 21
	v_readlane_b32 s8, v244, 0
	v_readlane_b32 s9, v244, 1
	s_nop 1
	s_add_u32 s4, s8, 0x4300000
	s_addc_u32 s5, s9, 0
	s_add_u32 s6, s8, 0x4b00000
	s_addc_u32 s7, s9, 0
	v_mov_b32_e32 v20, v245
	v_mov_b32_e32 v16, 0x2108422
.Lkvc_l5:
	v_mov_b32_e32 v21, s101
	v_mad_u32_u24 v21, v21, 0, v20
	v_and_b32_e32 v19, 31, v21
	v_lshrrev_b32_e32 v18, 5, v21
	v_mul_hi_u32 v17, v18, v16
	v_mul_u32_u24_e32 v23, 0x7c, v17
	v_sub_u32_e32 v18, v18, v23
	v_lshlrev_b32_e32 v19, 4, v19
	v_lshl_add_u32 v19, v18, 9, v19
	v_lshl_add_u32 v23, v17, 16, v19
	v_add_u32_e32 v22, 0x800, v23
	v_mov_b32_e32 v25, s101
	v_mad_u32_u24 v25, v25, 1, v20
	v_and_b32_e32 v19, 31, v25
	v_lshrrev_b32_e32 v18, 5, v25
	v_mul_hi_u32 v17, v18, v16
	v_mul_u32_u24_e32 v27, 0x7c, v17
	v_sub_u32_e32 v18, v18, v27
	v_lshlrev_b32_e32 v19, 4, v19
	v_lshl_add_u32 v19, v18, 9, v19
	v_lshl_add_u32 v27, v17, 16, v19
	v_add_u32_e32 v26, 0x800, v27
	v_mov_b32_e32 v29, s101
	v_mad_u32_u24 v29, v29, 2, v20
	v_and_b32_e32 v19, 31, v29
	v_lshrrev_b32_e32 v18, 5, v29
	v_mul_hi_u32 v17, v18, v16
	v_mul_u32_u24_e32 v31, 0x7c, v17
	v_sub_u32_e32 v18, v18, v31
	v_lshlrev_b32_e32 v19, 4, v19
	v_lshl_add_u32 v19, v18, 9, v19
	v_lshl_add_u32 v31, v17, 16, v19
	v_add_u32_e32 v30, 0x800, v31
	v_mov_b32_e32 v33, s101
	v_mad_u32_u24 v33, v33, 3, v20
	v_and_b32_e32 v19, 31, v33
	v_lshrrev_b32_e32 v18, 5, v33
	v_mul_hi_u32 v17, v18, v16
	v_mul_u32_u24_e32 v35, 0x7c, v17
	v_sub_u32_e32 v18, v18, v35
	v_lshlrev_b32_e32 v19, 4, v19
	v_lshl_add_u32 v19, v18, 9, v19
	v_lshl_add_u32 v35, v17, 16, v19
	v_add_u32_e32 v34, 0x800, v35
	v_mov_b32_e32 v37, s101
	v_mad_u32_u24 v37, v37, 4, v20
	v_and_b32_e32 v19, 31, v37
	v_lshrrev_b32_e32 v18, 5, v37
	v_mul_hi_u32 v17, v18, v16
	v_mul_u32_u24_e32 v39, 0x7c, v17
	v_sub_u32_e32 v18, v18, v39
	v_lshlrev_b32_e32 v19, 4, v19
	v_lshl_add_u32 v19, v18, 9, v19
	v_lshl_add_u32 v39, v17, 16, v19
	v_add_u32_e32 v38, 0x800, v39
	v_mov_b32_e32 v41, s101
	v_mad_u32_u24 v41, v41, 5, v20
	v_and_b32_e32 v19, 31, v41
	v_lshrrev_b32_e32 v18, 5, v41
	v_mul_hi_u32 v17, v18, v16
	v_mul_u32_u24_e32 v43, 0x7c, v17
	v_sub_u32_e32 v18, v18, v43
	v_lshlrev_b32_e32 v19, 4, v19
	v_lshl_add_u32 v19, v18, 9, v19
	v_lshl_add_u32 v43, v17, 16, v19
	v_add_u32_e32 v42, 0x800, v43
	v_cmp_gt_u32_e32 vcc, 0x7c000, v21
	s_and_saveexec_b64 s[10:11], vcc
	global_load_dwordx4 v[48:51], v22, s[12:13]
	global_load_dwordx4 v[52:55], v22, s[14:15]
	s_or_b64 exec, exec, s[10:11]
	v_cmp_gt_u32_e32 vcc, 0x7c000, v25
	s_and_saveexec_b64 s[10:11], vcc
	global_load_dwordx4 v[56:59], v26, s[12:13]
	global_load_dwordx4 v[60:63], v26, s[14:15]
	s_or_b64 exec, exec, s[10:11]
	v_cmp_gt_u32_e32 vcc, 0x7c000, v29
	s_and_saveexec_b64 s[10:11], vcc
	global_load_dwordx4 v[64:67], v30, s[12:13]
	global_load_dwordx4 v[68:71], v30, s[14:15]
	s_or_b64 exec, exec, s[10:11]
	v_cmp_gt_u32_e32 vcc, 0x7c000, v33
	s_and_saveexec_b64 s[10:11], vcc
	global_load_dwordx4 v[72:75], v34, s[12:13]
	global_load_dwordx4 v[76:79], v34, s[14:15]
	s_or_b64 exec, exec, s[10:11]
	v_cmp_gt_u32_e32 vcc, 0x7c000, v37
	s_and_saveexec_b64 s[10:11], vcc
	global_load_dwordx4 v[80:83], v38, s[12:13]
	global_load_dwordx4 v[84:87], v38, s[14:15]
	s_or_b64 exec, exec, s[10:11]
	v_cmp_gt_u32_e32 vcc, 0x7c000, v41
	s_and_saveexec_b64 s[10:11], vcc
	global_load_dwordx4 v[88:91], v42, s[12:13]
	global_load_dwordx4 v[92:95], v42, s[14:15]
	s_or_b64 exec, exec, s[10:11]
	s_waitcnt vmcnt(0)
	v_cmp_gt_u32_e32 vcc, 0x7c000, v21
	s_and_saveexec_b64 s[10:11], vcc
	global_store_dwordx4 v23, v[48:51], s[4:5]
	global_store_dwordx4 v23, v[52:55], s[6:7]
	s_or_b64 exec, exec, s[10:11]
	v_cmp_gt_u32_e32 vcc, 0x7c000, v25
	s_and_saveexec_b64 s[10:11], vcc
	global_store_dwordx4 v27, v[56:59], s[4:5]
	global_store_dwordx4 v27, v[60:63], s[6:7]
	s_or_b64 exec, exec, s[10:11]
	v_cmp_gt_u32_e32 vcc, 0x7c000, v29
	s_and_saveexec_b64 s[10:11], vcc
	global_store_dwordx4 v31, v[64:67], s[4:5]
	global_store_dwordx4 v31, v[68:71], s[6:7]
	s_or_b64 exec, exec, s[10:11]
	v_cmp_gt_u32_e32 vcc, 0x7c000, v33
	s_and_saveexec_b64 s[10:11], vcc
	global_store_dwordx4 v35, v[72:75], s[4:5]
	global_store_dwordx4 v35, v[76:79], s[6:7]
	s_or_b64 exec, exec, s[10:11]
	v_cmp_gt_u32_e32 vcc, 0x7c000, v37
	s_and_saveexec_b64 s[10:11], vcc
	global_store_dwordx4 v39, v[80:83], s[4:5]
	global_store_dwordx4 v39, v[84:87], s[6:7]
	s_or_b64 exec, exec, s[10:11]
	v_cmp_gt_u32_e32 vcc, 0x7c000, v41
	s_and_saveexec_b64 s[10:11], vcc
	global_store_dwordx4 v43, v[88:91], s[4:5]
	global_store_dwordx4 v43, v[92:95], s[6:7]
	s_or_b64 exec, exec, s[10:11]
	v_mov_b32_e32 v19, s101
	v_mad_u32_u24 v20, v19, 6, v20
	v_cmp_gt_u32_e32 vcc, 0x7c000, v20
	s_cbranch_vccnz .Lkvc_l5
	v_readlane_b32 s0, v246, 0
	v_readlane_b32 s1, v246, 1
	v_readlane_b32 s2, v246, 2
	v_readlane_b32 s3, v246, 3
	v_readlane_b32 s4, v246, 4
	v_readlane_b32 s5, v246, 5
	v_readlane_b32 s6, v246, 6
	v_readlane_b32 s7, v246, 7
	v_readlane_b32 s8, v246, 8
	v_readlane_b32 s9, v246, 9
	v_readlane_b32 s10, v246, 10
	v_readlane_b32 s11, v246, 11
	v_readlane_b32 s12, v246, 12
	v_readlane_b32 s13, v246, 13
	v_readlane_b32 s14, v246, 14
	v_readlane_b32 s15, v246, 15
	v_readlane_b32 s16, v246, 16
	v_readlane_b32 s17, v246, 17
	v_readlane_b32 s18, v246, 18
	v_readlane_b32 s19, v246, 19
	v_readlane_b32 s20, v246, 20
	v_readlane_b32 s21, v246, 21
	v_readlane_b32 s22, v246, 22
	v_readlane_b32 s23, v246, 23
	v_readlane_b32 s24, v246, 24
	v_readlane_b32 s25, v246, 25
	v_lshlrev_b32_e32 v1, 2, v0
	s_waitcnt vmcnt(0)
	s_barrier
